# 256x128 GEMM k-loops (phases 5,7,8) also use v_mfma_f32_16x16x32_bf16 + permlane swap back to the 32x32 accumulator layout
# baseline (speedup 1.0000x reference)
.LBB0_59:
	s_and_b32 s2, s2, 7
	v_readlane_b32 s4, v251, 7
	s_or_b32 s11, s2, s4
	s_lshl_b32 s10, s16, 7
	s_mul_i32 s2, s11, 0x160000
	s_add_u32 s4, s18, s2
	v_readlane_b32 s72, v250, 53
	s_addc_u32 s5, s19, 0
	s_mul_i32 s2, s16, 0xb0000
	v_readlane_b32 s84, v249, 1
	v_mov_b32_e32 v56, v200
	s_add_u32 s6, s84, s2
	s_movk_i32 s2, 0xb00
	v_ashrrev_i32_e32 v57, 2, v56
	v_lshlrev_b32_e32 v0, 3, v56
	s_waitcnt vmcnt(0)
	v_and_b32_e32 v188, 24, v0
	v_mad_i64_i32 v[0:1], s[8:9], v57, s2, 0
	v_lshlrev_b64 v[178:179], 1, v[0:1]
	v_add_u32_e32 v0, 64, v57
	v_mad_i64_i32 v[0:1], s[8:9], v0, s2, 0
	s_mul_hi_u32 s7, s10, 0x1600
	v_readlane_b32 s85, v249, 2
	v_lshlrev_b64 v[180:181], 1, v[0:1]
	v_add_u32_e32 v0, 0x80, v57
	s_addc_u32 s7, s85, s7
	v_lshlrev_b32_e32 v196, 1, v188
	v_mad_i64_i32 v[44:45], s[8:9], v0, s2, 0
	v_add_u32_e32 v0, 0xc0, v57
	v_lshl_add_u64 v[176:177], s[4:5], 0, v[196:197]
	v_mad_i64_i32 v[48:49], s[8:9], v0, s2, 0
	v_lshl_add_u64 v[182:183], s[6:7], 0, v[196:197]
	v_lshl_add_u64 v[40:41], v[176:177], 0, v[178:179]
	v_lshl_add_u64 v[42:43], v[176:177], 0, v[180:181]
	v_lshl_add_u64 v[46:47], v[44:45], 1, v[176:177]
	v_lshl_add_u64 v[50:51], v[48:49], 1, v[176:177]
	v_lshl_add_u64 v[52:53], v[182:183], 0, v[178:179]
	v_lshl_add_u64 v[54:55], v[182:183], 0, v[180:181]
	v_and_b32_e32 v192, 63, v200
	v_readfirstlane_b32 s44, v200
	v_lshrrev_b32_e32 v193, 2, v192
	v_and_b32_e32 v194, 3, v192
	v_lshrrev_b32_e32 v201, 4, v192
	s_lshr_b32 s44, s44, 6
	v_xor_b32_e32 v206, v194, v201
	v_lshlrev_b32_e32 v206, 4, v206
	s_lshl_b32 s32, s44, 6
	v_add_u32_e32 v212, s32, v193
	v_mul_u32_u24_e32 v212, 0x1600, v212
	v_add_u32_e32 v234, v212, v206
	v_add_u32_e32 v235, 0x16000, v234
	v_add_u32_e32 v236, 0x2c000, v234
	v_add_u32_e32 v237, 0x42000, v234
	s_lshl_b32 s32, s44, 5
	v_add_u32_e32 v212, s32, v193
	v_mul_u32_u24_e32 v212, 0x1600, v212
	v_add_u32_e32 v238, v212, v206
	v_add_u32_e32 v239, 0x16000, v238
	v_and_b32_e32 v193, 15, v192
	v_lshrrev_b32_e32 v194, 4, v192
	v_bfe_u32 v201, v192, 2, 2
	v_xor_b32_e32 v206, v194, v201
	v_lshlrev_b32_e32 v206, 4, v206
	v_lshl_add_u32 v206, v193, 6, v206
	s_lshr_b32 s32, s44, 1
	s_lshl_b32 s32, s32, 13
	v_add_u32_e32 v240, s32, v206
	v_xor_b32_e32 v241, 32, v240
	s_and_b32 s32, s44, 1
	s_lshl_b32 s32, s32, 12
	s_add_u32 s32, s32, 0x4000
	v_add_u32_e32 v242, s32, v206
	v_xor_b32_e32 v243, 32, v242
	s_lshl_b32 s46, s44, 12
	s_lshl_b32 s47, s44, 11
	s_add_u32 s47, s47, 0x4000
	s_mov_b32 s40, s4
	s_mov_b32 s41, s5
	s_mov_b32 s42, s6
	s_mov_b32 s43, s7
	s_add_u32 m0, s46, 0x0
	s_nop 0
	global_load_lds_dwordx4 v234, s[40:41]
	s_add_u32 m0, m0, 0x400
	s_nop 0
	global_load_lds_dwordx4 v235, s[40:41]
	s_add_u32 m0, m0, 0x400
	s_nop 0
	global_load_lds_dwordx4 v236, s[40:41]
	s_add_u32 m0, m0, 0x400
	s_nop 0
	global_load_lds_dwordx4 v237, s[40:41]
	s_add_u32 m0, s47, 0x0
	s_nop 0
	global_load_lds_dwordx4 v238, s[42:43]
	s_add_u32 m0, m0, 0x400
	s_nop 0
	global_load_lds_dwordx4 v239, s[42:43]
	s_add_u32 s40, s40, 64
	s_addc_u32 s41, s41, 0
	s_add_u32 s42, s42, 64
	s_addc_u32 s43, s43, 0
	s_add_u32 m0, s46, 0x6000
	s_nop 0
	global_load_lds_dwordx4 v234, s[40:41]
	s_add_u32 m0, m0, 0x400
	s_nop 0
	global_load_lds_dwordx4 v235, s[40:41]
	s_add_u32 m0, m0, 0x400
	s_nop 0
	global_load_lds_dwordx4 v236, s[40:41]
	s_add_u32 m0, m0, 0x400
	s_nop 0
	global_load_lds_dwordx4 v237, s[40:41]
	s_add_u32 m0, s47, 0x6000
	s_nop 0
	global_load_lds_dwordx4 v238, s[42:43]
	s_add_u32 m0, m0, 0x400
	s_nop 0
	global_load_lds_dwordx4 v239, s[42:43]
	s_add_u32 s40, s40, 64
	s_addc_u32 s41, s41, 0
	s_add_u32 s42, s42, 64
	s_addc_u32 s43, s43, 0
	s_mov_b32 s45, 0xc000
	s_mov_b32 s49, 0
	v_and_b32_e32 v58, 0xfffff9f, v56
	v_lshrrev_b32_e32 v59, 1, v56
	v_and_b32_e32 v56, 0x5f, v56
	s_movk_i32 s2, 0x50
	v_and_b32_e32 v59, 16, v59
	v_mad_u32_u24 v56, v56, s2, 0
	v_mul_lo_u32 v57, v57, s2
	v_mul_lo_u32 v58, v58, s2
	v_add_u32_e32 v189, v56, v59
	v_add_u32_e32 v56, 0, v196
	v_mov_b32_e32 v0, 0
	v_add_u32_e32 v58, 0, v58
	v_add_u32_e32 v191, v56, v57
	s_mov_b32 s17, 64
	s_mov_b32 s18, 0
	v_mov_b32_e32 v1, v0
	v_mov_b32_e32 v2, v0
	v_mov_b32_e32 v3, v0
	v_mov_b32_e32 v4, v0
	v_mov_b32_e32 v5, v0
	v_mov_b32_e32 v6, v0
	v_mov_b32_e32 v7, v0
	v_mov_b32_e32 v8, v0
	v_mov_b32_e32 v9, v0
	v_mov_b32_e32 v10, v0
	v_mov_b32_e32 v11, v0
	v_mov_b32_e32 v12, v0
	v_mov_b32_e32 v13, v0
	v_mov_b32_e32 v14, v0
	v_mov_b32_e32 v15, v0
	v_lshlrev_b64 v[184:185], 1, v[44:45]
	v_lshlrev_b64 v[186:187], 1, v[48:49]
	v_add_u32_e32 v190, v58, v59
	v_mov_b32_e32 v40, v0
	v_mov_b32_e32 v41, v0
	v_mov_b32_e32 v42, v0
	v_mov_b32_e32 v43, v0
	v_mov_b32_e32 v44, v0
	v_mov_b32_e32 v45, v0
	v_mov_b32_e32 v46, v0
	v_mov_b32_e32 v47, v0
	v_mov_b32_e32 v16, v0
	v_mov_b32_e32 v17, v0
	v_mov_b32_e32 v18, v0
	v_mov_b32_e32 v19, v0
	v_mov_b32_e32 v20, v0
	v_mov_b32_e32 v21, v0
	v_mov_b32_e32 v22, v0
	v_mov_b32_e32 v23, v0
	v_mov_b32_e32 v24, v0
	v_mov_b32_e32 v25, v0
	v_mov_b32_e32 v26, v0
	v_mov_b32_e32 v27, v0
	v_mov_b32_e32 v28, v0
	v_mov_b32_e32 v29, v0
	v_mov_b32_e32 v30, v0
	v_mov_b32_e32 v31, v0
	v_mov_b32_e32 v32, v0
	v_mov_b32_e32 v33, v0
	v_mov_b32_e32 v34, v0
	v_mov_b32_e32 v35, v0
	v_mov_b32_e32 v36, v0
	v_mov_b32_e32 v37, v0
	v_mov_b32_e32 v38, v0
	v_mov_b32_e32 v39, v0
	v_mov_b32_e32 v48, v0
	v_mov_b32_e32 v49, v0
	v_mov_b32_e32 v50, v0
	v_mov_b32_e32 v51, v0
	v_mov_b32_e32 v52, v0
	v_mov_b32_e32 v53, v0
	v_mov_b32_e32 v54, v0
	v_mov_b32_e32 v55, v0
	v_mov_b32_e32 v56, v0
	v_mov_b32_e32 v57, v0
	v_mov_b32_e32 v58, v0
	v_mov_b32_e32 v59, v0
	v_mov_b32_e32 v60, v0
	v_mov_b32_e32 v61, v0
	v_mov_b32_e32 v62, v0
	v_mov_b32_e32 v63, v0
	v_mov_b32_e32 v64, v0
	v_mov_b32_e32 v65, v0
	v_mov_b32_e32 v66, v0
	v_mov_b32_e32 v67, v0
	v_mov_b32_e32 v68, v0
	v_mov_b32_e32 v69, v0
	v_mov_b32_e32 v70, v0
	v_mov_b32_e32 v71, v0
	v_mov_b32_e32 v72, v0
	v_mov_b32_e32 v73, v0
	v_mov_b32_e32 v74, v0
	v_mov_b32_e32 v75, v0
	v_mov_b32_e32 v76, v0
	v_mov_b32_e32 v77, v0
	v_mov_b32_e32 v78, v0
	v_mov_b32_e32 v79, v0
	v_mov_b32_e32 v80, v0
	v_mov_b32_e32 v81, v0
	v_mov_b32_e32 v82, v0
	v_mov_b32_e32 v83, v0
	v_mov_b32_e32 v84, v0
	v_mov_b32_e32 v85, v0
	v_mov_b32_e32 v86, v0
	v_mov_b32_e32 v87, v0
	v_mov_b32_e32 v88, v0
	v_mov_b32_e32 v89, v0
	v_mov_b32_e32 v90, v0
	v_mov_b32_e32 v91, v0
	v_mov_b32_e32 v92, v0
	v_mov_b32_e32 v93, v0
	v_mov_b32_e32 v94, v0
	v_mov_b32_e32 v95, v0
	v_mov_b32_e32 v96, v0
	v_mov_b32_e32 v97, v0
	v_mov_b32_e32 v98, v0
	v_mov_b32_e32 v99, v0
	v_mov_b32_e32 v100, v0
	v_mov_b32_e32 v101, v0
	v_mov_b32_e32 v102, v0
	v_mov_b32_e32 v103, v0
	v_mov_b32_e32 v104, v0
	v_mov_b32_e32 v105, v0
	v_mov_b32_e32 v106, v0
	v_mov_b32_e32 v107, v0
	v_mov_b32_e32 v108, v0
	v_mov_b32_e32 v109, v0
	v_mov_b32_e32 v110, v0
	v_mov_b32_e32 v111, v0
	v_mov_b32_e32 v112, v0
	v_mov_b32_e32 v113, v0
	v_mov_b32_e32 v114, v0
	v_mov_b32_e32 v115, v0
	v_mov_b32_e32 v116, v0
	v_mov_b32_e32 v117, v0
	v_mov_b32_e32 v118, v0
	v_mov_b32_e32 v119, v0
	v_mov_b32_e32 v120, v0
	v_mov_b32_e32 v121, v0
	v_mov_b32_e32 v122, v0
	v_mov_b32_e32 v123, v0
	v_mov_b32_e32 v124, v0
	v_mov_b32_e32 v125, v0
	v_mov_b32_e32 v126, v0
	v_mov_b32_e32 v127, v0
	v_readlane_b32 s73, v250, 54
	v_readlane_b32 s74, v250, 55
	v_readlane_b32 s75, v250, 56
	v_readlane_b32 s76, v250, 57
	v_readlane_b32 s77, v250, 58
	v_readlane_b32 s78, v250, 59
	v_readlane_b32 s79, v250, 60
	v_readlane_b32 s80, v250, 61
	v_readlane_b32 s81, v250, 62
	v_readlane_b32 s82, v250, 63
	v_readlane_b32 s83, v249, 0
	v_readlane_b32 s86, v249, 3
	v_readlane_b32 s87, v249, 4
	s_waitcnt vmcnt(6)
	s_waitcnt lgkmcnt(0)
	v_readlane_b32 s44, v251, 5
	s_nop 0
	s_bitcmp1_b32 s44, 5
	s_cbranch_scc0 .Lnoprio_1
	s_setprio 2

.LBB0_61:
	ds_read_b128 v[128:131], v242
	ds_read_b128 v[144:147], v240
	ds_read_b128 v[132:135], v242 offset:1024
	ds_read_b128 v[148:151], v240 offset:1024
	ds_read_b128 v[136:139], v242 offset:2048
	ds_read_b128 v[140:143], v242 offset:3072
	ds_read_b128 v[152:155], v240 offset:2048
	ds_read_b128 v[156:159], v240 offset:3072
	ds_read_b128 v[160:163], v240 offset:4096
	ds_read_b128 v[164:167], v240 offset:5120
	ds_read_b128 v[168:171], v240 offset:6144
	ds_read_b128 v[172:175], v240 offset:7168
	s_waitcnt lgkmcnt(10)
	v_mfma_f32_16x16x32_bf16 v[112:115], v[128:131], v[144:147], v[112:115]
	s_add_u32 m0, s46, s45
	s_waitcnt lgkmcnt(9)
	v_mfma_f32_16x16x32_bf16 v[120:123], v[132:135], v[144:147], v[120:123]
	s_waitcnt lgkmcnt(8)
	v_mfma_f32_16x16x32_bf16 v[116:119], v[128:131], v[148:151], v[116:119]
	v_mfma_f32_16x16x32_bf16 v[124:127], v[132:135], v[148:151], v[124:127]
	global_load_lds_dwordx4 v234, s[40:41]
	s_waitcnt lgkmcnt(7)
	v_mfma_f32_16x16x32_bf16 v[96:99], v[136:139], v[144:147], v[96:99]
	s_add_u32 m0, m0, 0x400
	v_mfma_f32_16x16x32_bf16 v[100:103], v[136:139], v[148:151], v[100:103]
	s_waitcnt lgkmcnt(6)
	v_mfma_f32_16x16x32_bf16 v[104:107], v[140:143], v[144:147], v[104:107]
	v_mfma_f32_16x16x32_bf16 v[108:111], v[140:143], v[148:151], v[108:111]
	global_load_lds_dwordx4 v235, s[40:41]
	s_waitcnt lgkmcnt(5)
	v_mfma_f32_16x16x32_bf16 v[80:83], v[128:131], v[152:155], v[80:83]
	s_add_u32 m0, m0, 0x400
	v_mfma_f32_16x16x32_bf16 v[88:91], v[132:135], v[152:155], v[88:91]
	v_mfma_f32_16x16x32_bf16 v[64:67], v[136:139], v[152:155], v[64:67]
	v_mfma_f32_16x16x32_bf16 v[72:75], v[140:143], v[152:155], v[72:75]
	global_load_lds_dwordx4 v236, s[40:41]
	s_waitcnt lgkmcnt(4)
	v_mfma_f32_16x16x32_bf16 v[84:87], v[128:131], v[156:159], v[84:87]
	s_add_u32 m0, m0, 0x400
	v_mfma_f32_16x16x32_bf16 v[92:95], v[132:135], v[156:159], v[92:95]
	v_mfma_f32_16x16x32_bf16 v[68:71], v[136:139], v[156:159], v[68:71]
	v_mfma_f32_16x16x32_bf16 v[76:79], v[140:143], v[156:159], v[76:79]
	global_load_lds_dwordx4 v237, s[40:41]
	s_waitcnt lgkmcnt(3)
	v_mfma_f32_16x16x32_bf16 v[48:51], v[128:131], v[160:163], v[48:51]
	s_add_u32 m0, s47, s45
	v_mfma_f32_16x16x32_bf16 v[56:59], v[132:135], v[160:163], v[56:59]
	v_mfma_f32_16x16x32_bf16 v[32:35], v[136:139], v[160:163], v[32:35]
	v_mfma_f32_16x16x32_bf16 v[40:43], v[140:143], v[160:163], v[40:43]
	global_load_lds_dwordx4 v238, s[42:43]
	s_waitcnt lgkmcnt(2)
	v_mfma_f32_16x16x32_bf16 v[52:55], v[128:131], v[164:167], v[52:55]
	s_add_u32 m0, m0, 0x400
	v_mfma_f32_16x16x32_bf16 v[60:63], v[132:135], v[164:167], v[60:63]
	v_mfma_f32_16x16x32_bf16 v[36:39], v[136:139], v[164:167], v[36:39]
	v_mfma_f32_16x16x32_bf16 v[44:47], v[140:143], v[164:167], v[44:47]
	global_load_lds_dwordx4 v239, s[42:43]
	s_waitcnt lgkmcnt(1)
	v_mfma_f32_16x16x32_bf16 v[16:19], v[128:131], v[168:171], v[16:19]
	v_mfma_f32_16x16x32_bf16 v[24:27], v[132:135], v[168:171], v[24:27]
	s_mov_b32 s32, 0x6000
	s_cmp_eq_u32 s49, 0xc000
	s_cselect_b32 s32, 0xffff4000, s32
	s_add_u32 s49, s49, s32
	v_add_u32_e32 v240, s32, v240
	v_add_u32_e32 v242, s32, v242
	s_add_u32 s45, s45, 0x6000
	s_cmp_eq_u32 s45, 0x12000
	s_cselect_b32 s45, 0, s45
	s_add_u32 s40, s40, 64
	s_addc_u32 s41, s41, 0
	s_add_u32 s42, s42, 64
	s_addc_u32 s43, s43, 0
	v_mfma_f32_16x16x32_bf16 v[0:3], v[136:139], v[168:171], v[0:3]
	v_mfma_f32_16x16x32_bf16 v[8:11], v[140:143], v[168:171], v[8:11]
	s_waitcnt lgkmcnt(0)
	v_mfma_f32_16x16x32_bf16 v[20:23], v[128:131], v[172:175], v[20:23]
	v_mfma_f32_16x16x32_bf16 v[28:31], v[132:135], v[172:175], v[28:31]
	v_mfma_f32_16x16x32_bf16 v[4:7], v[136:139], v[172:175], v[4:7]
	v_mfma_f32_16x16x32_bf16 v[12:15], v[140:143], v[172:175], v[12:15]
	s_add_u32 s18, s18, 1
	s_waitcnt vmcnt(6)
	s_cmp_lt_u32 s18, 86
	s_barrier
	s_cbranch_scc1 .LBB0_61
.Lp8_tail:
	ds_read_b128 v[128:131], v242
	ds_read_b128 v[144:147], v240
	ds_read_b128 v[132:135], v242 offset:1024
	ds_read_b128 v[148:151], v240 offset:1024
	ds_read_b128 v[136:139], v242 offset:2048
	ds_read_b128 v[140:143], v242 offset:3072
	ds_read_b128 v[152:155], v240 offset:2048
	ds_read_b128 v[156:159], v240 offset:3072
	ds_read_b128 v[160:163], v240 offset:4096
	ds_read_b128 v[164:167], v240 offset:5120
	ds_read_b128 v[168:171], v240 offset:6144
	ds_read_b128 v[172:175], v240 offset:7168
	s_waitcnt lgkmcnt(10)
	v_mfma_f32_16x16x32_bf16 v[112:115], v[128:131], v[144:147], v[112:115]
	s_waitcnt lgkmcnt(9)
	v_mfma_f32_16x16x32_bf16 v[120:123], v[132:135], v[144:147], v[120:123]
	s_waitcnt lgkmcnt(8)
	v_mfma_f32_16x16x32_bf16 v[116:119], v[128:131], v[148:151], v[116:119]
	v_mfma_f32_16x16x32_bf16 v[124:127], v[132:135], v[148:151], v[124:127]
	s_waitcnt lgkmcnt(7)
	v_mfma_f32_16x16x32_bf16 v[96:99], v[136:139], v[144:147], v[96:99]
	v_mfma_f32_16x16x32_bf16 v[100:103], v[136:139], v[148:151], v[100:103]
	s_waitcnt lgkmcnt(6)
	v_mfma_f32_16x16x32_bf16 v[104:107], v[140:143], v[144:147], v[104:107]
	v_mfma_f32_16x16x32_bf16 v[108:111], v[140:143], v[148:151], v[108:111]
	s_waitcnt lgkmcnt(5)
	v_mfma_f32_16x16x32_bf16 v[80:83], v[128:131], v[152:155], v[80:83]
	v_mfma_f32_16x16x32_bf16 v[88:91], v[132:135], v[152:155], v[88:91]
	v_mfma_f32_16x16x32_bf16 v[64:67], v[136:139], v[152:155], v[64:67]
	v_mfma_f32_16x16x32_bf16 v[72:75], v[140:143], v[152:155], v[72:75]
	s_waitcnt lgkmcnt(4)
	v_mfma_f32_16x16x32_bf16 v[84:87], v[128:131], v[156:159], v[84:87]
	v_mfma_f32_16x16x32_bf16 v[92:95], v[132:135], v[156:159], v[92:95]
	v_mfma_f32_16x16x32_bf16 v[68:71], v[136:139], v[156:159], v[68:71]
	v_mfma_f32_16x16x32_bf16 v[76:79], v[140:143], v[156:159], v[76:79]
	s_waitcnt lgkmcnt(3)
	v_mfma_f32_16x16x32_bf16 v[48:51], v[128:131], v[160:163], v[48:51]
	v_mfma_f32_16x16x32_bf16 v[56:59], v[132:135], v[160:163], v[56:59]
	v_mfma_f32_16x16x32_bf16 v[32:35], v[136:139], v[160:163], v[32:35]
	v_mfma_f32_16x16x32_bf16 v[40:43], v[140:143], v[160:163], v[40:43]
	s_waitcnt lgkmcnt(2)
	v_mfma_f32_16x16x32_bf16 v[52:55], v[128:131], v[164:167], v[52:55]
	v_mfma_f32_16x16x32_bf16 v[60:63], v[132:135], v[164:167], v[60:63]
	v_mfma_f32_16x16x32_bf16 v[36:39], v[136:139], v[164:167], v[36:39]
	v_mfma_f32_16x16x32_bf16 v[44:47], v[140:143], v[164:167], v[44:47]
	s_waitcnt lgkmcnt(1)
	v_mfma_f32_16x16x32_bf16 v[16:19], v[128:131], v[168:171], v[16:19]
	v_mfma_f32_16x16x32_bf16 v[24:27], v[132:135], v[168:171], v[24:27]
	s_mov_b32 s32, 0x6000
	s_cmp_eq_u32 s49, 0xc000
	s_cselect_b32 s32, 0xffff4000, s32
	s_add_u32 s49, s49, s32
	v_add_u32_e32 v240, s32, v240
	v_add_u32_e32 v242, s32, v242
	v_mfma_f32_16x16x32_bf16 v[0:3], v[136:139], v[168:171], v[0:3]
	v_mfma_f32_16x16x32_bf16 v[8:11], v[140:143], v[168:171], v[8:11]
	s_waitcnt lgkmcnt(0)
	v_mfma_f32_16x16x32_bf16 v[20:23], v[128:131], v[172:175], v[20:23]
	v_mfma_f32_16x16x32_bf16 v[28:31], v[132:135], v[172:175], v[28:31]
	v_mfma_f32_16x16x32_bf16 v[4:7], v[136:139], v[172:175], v[4:7]
	v_mfma_f32_16x16x32_bf16 v[12:15], v[140:143], v[172:175], v[12:15]
	s_add_u32 s18, s18, 1
	s_waitcnt vmcnt(0)
	s_cmp_lt_u32 s18, 88
	s_barrier
	s_cbranch_scc1 .Lp8_tail
	s_nop 7
	s_nop 7
	v_permlane16_swap_b32_e32 v112, v116
	v_permlane16_swap_b32_e32 v113, v117
	v_permlane16_swap_b32_e32 v114, v118
	v_permlane16_swap_b32_e32 v115, v119
	v_permlane16_swap_b32_e32 v120, v124
	v_permlane16_swap_b32_e32 v121, v125
	v_permlane16_swap_b32_e32 v122, v126
	v_permlane16_swap_b32_e32 v123, v127
	v_permlane16_swap_b32_e32 v96, v100
	v_permlane16_swap_b32_e32 v97, v101
	v_permlane16_swap_b32_e32 v98, v102
	v_permlane16_swap_b32_e32 v99, v103
	v_permlane16_swap_b32_e32 v104, v108
	v_permlane16_swap_b32_e32 v105, v109
	v_permlane16_swap_b32_e32 v106, v110
	v_permlane16_swap_b32_e32 v107, v111
	v_permlane16_swap_b32_e32 v80, v84
	v_permlane16_swap_b32_e32 v81, v85
	v_permlane16_swap_b32_e32 v82, v86
	v_permlane16_swap_b32_e32 v83, v87
	v_permlane16_swap_b32_e32 v88, v92
	v_permlane16_swap_b32_e32 v89, v93
	v_permlane16_swap_b32_e32 v90, v94
	v_permlane16_swap_b32_e32 v91, v95
	v_permlane16_swap_b32_e32 v64, v68
	v_permlane16_swap_b32_e32 v65, v69
	v_permlane16_swap_b32_e32 v66, v70
	v_permlane16_swap_b32_e32 v67, v71
	v_permlane16_swap_b32_e32 v72, v76
	v_permlane16_swap_b32_e32 v73, v77
	v_permlane16_swap_b32_e32 v74, v78
	v_permlane16_swap_b32_e32 v75, v79
	v_permlane16_swap_b32_e32 v48, v52
	v_permlane16_swap_b32_e32 v49, v53
	v_permlane16_swap_b32_e32 v50, v54
	v_permlane16_swap_b32_e32 v51, v55
	v_permlane16_swap_b32_e32 v56, v60
	v_permlane16_swap_b32_e32 v57, v61
	v_permlane16_swap_b32_e32 v58, v62
	v_permlane16_swap_b32_e32 v59, v63
	v_permlane16_swap_b32_e32 v32, v36
	v_permlane16_swap_b32_e32 v33, v37
	v_permlane16_swap_b32_e32 v34, v38
	v_permlane16_swap_b32_e32 v35, v39
	v_permlane16_swap_b32_e32 v40, v44
	v_permlane16_swap_b32_e32 v41, v45
	v_permlane16_swap_b32_e32 v42, v46
	v_permlane16_swap_b32_e32 v43, v47
	v_permlane16_swap_b32_e32 v16, v20
	v_permlane16_swap_b32_e32 v17, v21
	v_permlane16_swap_b32_e32 v18, v22
	v_permlane16_swap_b32_e32 v19, v23
	v_permlane16_swap_b32_e32 v24, v28
	v_permlane16_swap_b32_e32 v25, v29
	v_permlane16_swap_b32_e32 v26, v30
	v_permlane16_swap_b32_e32 v27, v31
	v_permlane16_swap_b32_e32 v0, v4
	v_permlane16_swap_b32_e32 v1, v5
	v_permlane16_swap_b32_e32 v2, v6
	v_permlane16_swap_b32_e32 v3, v7
	v_permlane16_swap_b32_e32 v8, v12
	v_permlane16_swap_b32_e32 v9, v13
	v_permlane16_swap_b32_e32 v10, v14
	v_permlane16_swap_b32_e32 v11, v15
	v_permlane32_swap_b32_e32 v112, v116
	v_permlane32_swap_b32_e32 v113, v117
	v_permlane32_swap_b32_e32 v114, v118
	v_permlane32_swap_b32_e32 v115, v119
	v_permlane32_swap_b32_e32 v120, v124
	v_permlane32_swap_b32_e32 v121, v125
	v_permlane32_swap_b32_e32 v122, v126
	v_permlane32_swap_b32_e32 v123, v127
	v_permlane32_swap_b32_e32 v96, v100
	v_permlane32_swap_b32_e32 v97, v101
	v_permlane32_swap_b32_e32 v98, v102
	v_permlane32_swap_b32_e32 v99, v103
	v_permlane32_swap_b32_e32 v104, v108
	v_permlane32_swap_b32_e32 v105, v109
	v_permlane32_swap_b32_e32 v106, v110
	v_permlane32_swap_b32_e32 v107, v111
	v_permlane32_swap_b32_e32 v80, v84
	v_permlane32_swap_b32_e32 v81, v85
	v_permlane32_swap_b32_e32 v82, v86
	v_permlane32_swap_b32_e32 v83, v87
	v_permlane32_swap_b32_e32 v88, v92
	v_permlane32_swap_b32_e32 v89, v93
	v_permlane32_swap_b32_e32 v90, v94
	v_permlane32_swap_b32_e32 v91, v95
	v_permlane32_swap_b32_e32 v64, v68
	v_permlane32_swap_b32_e32 v65, v69
	v_permlane32_swap_b32_e32 v66, v70
	v_permlane32_swap_b32_e32 v67, v71
	v_permlane32_swap_b32_e32 v72, v76
	v_permlane32_swap_b32_e32 v73, v77
	v_permlane32_swap_b32_e32 v74, v78
	v_permlane32_swap_b32_e32 v75, v79
	v_permlane32_swap_b32_e32 v48, v52
	v_permlane32_swap_b32_e32 v49, v53
	v_permlane32_swap_b32_e32 v50, v54
	v_permlane32_swap_b32_e32 v51, v55
	v_permlane32_swap_b32_e32 v56, v60
	v_permlane32_swap_b32_e32 v57, v61
	v_permlane32_swap_b32_e32 v58, v62
	v_permlane32_swap_b32_e32 v59, v63
	v_permlane32_swap_b32_e32 v32, v36
	v_permlane32_swap_b32_e32 v33, v37
	v_permlane32_swap_b32_e32 v34, v38
	v_permlane32_swap_b32_e32 v35, v39
	v_permlane32_swap_b32_e32 v40, v44
	v_permlane32_swap_b32_e32 v41, v45
	v_permlane32_swap_b32_e32 v42, v46
	v_permlane32_swap_b32_e32 v43, v47
	v_permlane32_swap_b32_e32 v16, v20
	v_permlane32_swap_b32_e32 v17, v21
	v_permlane32_swap_b32_e32 v18, v22
	v_permlane32_swap_b32_e32 v19, v23
	v_permlane32_swap_b32_e32 v24, v28
	v_permlane32_swap_b32_e32 v25, v29
	v_permlane32_swap_b32_e32 v26, v30
	v_permlane32_swap_b32_e32 v27, v31
	v_permlane32_swap_b32_e32 v0, v4
	v_permlane32_swap_b32_e32 v1, v5
	v_permlane32_swap_b32_e32 v2, v6
	v_permlane32_swap_b32_e32 v3, v7
	v_permlane32_swap_b32_e32 v8, v12
	v_permlane32_swap_b32_e32 v9, v13
	v_permlane32_swap_b32_e32 v10, v14
	v_permlane32_swap_b32_e32 v11, v15
	s_setprio 0
	s_branch .LBB0_63

.LBB0_75:
	s_and_b32 s4, s2, 7
	v_readlane_b32 s5, v251, 7
	s_or_b32 s11, s4, s5
	v_readlane_b32 s16, v250, 53
	s_lshr_b32 s10, s2, 3
	s_lshl_b32 s2, s11, 19
	v_readlane_b32 s22, v250, 59
	v_mov_b32_e32 v13, v200
	v_readlane_b32 s23, v250, 60
	s_add_u32 s4, s22, s2
	v_readlane_b32 s26, v250, 63
	v_ashrrev_i32_e32 v38, 2, v13
	v_lshlrev_b32_e32 v0, 3, v13
	s_addc_u32 s5, s23, 0
	s_lshl_b32 s2, s10, 18
	s_waitcnt vmcnt(0)
	v_and_b32_e32 v188, 24, v0
	v_add_u32_e32 v46, 0x80, v38
	v_readlane_b32 s27, v249, 0
	s_add_u32 s6, s26, s2
	v_lshlrev_b32_e32 v196, 1, v188
	v_add_u32_e32 v42, 64, v38
	v_ashrrev_i32_e32 v47, 31, v46
	v_add_u32_e32 v50, 0xc0, v38
	s_addc_u32 s7, s27, 0
	v_lshl_add_u64 v[176:177], s[4:5], 0, v[196:197]
	v_ashrrev_i32_e32 v39, 31, v38
	v_ashrrev_i32_e32 v43, 31, v42
	v_lshlrev_b64 v[4:5], 11, v[46:47]
	v_ashrrev_i32_e32 v51, 31, v50
	v_lshlrev_b64 v[0:1], 11, v[38:39]
	v_lshlrev_b64 v[2:3], 11, v[42:43]
	v_lshl_add_u64 v[48:49], v[176:177], 0, v[4:5]
	v_lshlrev_b64 v[4:5], 11, v[50:51]
	v_lshl_add_u64 v[178:179], s[6:7], 0, v[196:197]
	v_lshl_add_u64 v[40:41], v[176:177], 0, v[0:1]
	v_lshl_add_u64 v[44:45], v[176:177], 0, v[2:3]
	v_lshl_add_u64 v[52:53], v[176:177], 0, v[4:5]
	v_lshl_add_u64 v[54:55], v[178:179], 0, v[0:1]
	v_lshl_add_u64 v[56:57], v[178:179], 0, v[2:3]
	v_and_b32_e32 v192, 63, v200
	v_readfirstlane_b32 s44, v200
	v_lshrrev_b32_e32 v193, 2, v192
	v_and_b32_e32 v194, 3, v192
	v_lshrrev_b32_e32 v201, 4, v192
	s_lshr_b32 s44, s44, 6
	v_xor_b32_e32 v206, v194, v201
	v_lshlrev_b32_e32 v206, 4, v206
	s_lshl_b32 s32, s44, 6
	v_add_u32_e32 v212, s32, v193
	v_lshlrev_b32_e32 v212, 11, v212
	v_add_u32_e32 v234, v212, v206
	v_add_u32_e32 v235, 0x8000, v234
	v_add_u32_e32 v236, 0x10000, v234
	v_add_u32_e32 v237, 0x18000, v234
	s_lshl_b32 s32, s44, 5
	v_add_u32_e32 v212, s32, v193
	v_lshlrev_b32_e32 v212, 11, v212
	v_add_u32_e32 v238, v212, v206
	v_add_u32_e32 v239, 0x8000, v238
	v_and_b32_e32 v193, 15, v192
	v_lshrrev_b32_e32 v194, 4, v192
	v_bfe_u32 v201, v192, 2, 2
	v_xor_b32_e32 v206, v194, v201
	v_lshlrev_b32_e32 v206, 4, v206
	v_lshl_add_u32 v206, v193, 6, v206
	s_lshr_b32 s32, s44, 1
	s_lshl_b32 s32, s32, 13
	v_add_u32_e32 v240, s32, v206
	v_xor_b32_e32 v241, 32, v240
	s_and_b32 s32, s44, 1
	s_lshl_b32 s32, s32, 12
	s_add_u32 s32, s32, 0x4000
	v_add_u32_e32 v242, s32, v206
	v_xor_b32_e32 v243, 32, v242
	s_lshl_b32 s46, s44, 12
	s_lshl_b32 s47, s44, 11
	s_add_u32 s47, s47, 0x4000
	s_mov_b32 s40, s4
	s_mov_b32 s41, s5
	s_mov_b32 s42, s6
	s_mov_b32 s43, s7
	s_add_u32 m0, s46, 0x0
	s_nop 0
	global_load_lds_dwordx4 v234, s[40:41]
	s_add_u32 m0, m0, 0x400
	s_nop 0
	global_load_lds_dwordx4 v235, s[40:41]
	s_add_u32 m0, m0, 0x400
	s_nop 0
	global_load_lds_dwordx4 v236, s[40:41]
	s_add_u32 m0, m0, 0x400
	s_nop 0
	global_load_lds_dwordx4 v237, s[40:41]
	s_add_u32 m0, s47, 0x0
	s_nop 0
	global_load_lds_dwordx4 v238, s[42:43]
	s_add_u32 m0, m0, 0x400
	s_nop 0
	global_load_lds_dwordx4 v239, s[42:43]
	s_add_u32 s40, s40, 64
	s_addc_u32 s41, s41, 0
	s_add_u32 s42, s42, 64
	s_addc_u32 s43, s43, 0
	s_add_u32 m0, s46, 0x6000
	s_nop 0
	global_load_lds_dwordx4 v234, s[40:41]
	s_add_u32 m0, m0, 0x400
	s_nop 0
	global_load_lds_dwordx4 v235, s[40:41]
	s_add_u32 m0, m0, 0x400
	s_nop 0
	global_load_lds_dwordx4 v236, s[40:41]
	s_add_u32 m0, m0, 0x400
	s_nop 0
	global_load_lds_dwordx4 v237, s[40:41]
	s_add_u32 m0, s47, 0x6000
	s_nop 0
	global_load_lds_dwordx4 v238, s[42:43]
	s_add_u32 m0, m0, 0x400
	s_nop 0
	global_load_lds_dwordx4 v239, s[42:43]
	s_add_u32 s40, s40, 64
	s_addc_u32 s41, s41, 0
	s_add_u32 s42, s42, 64
	s_addc_u32 s43, s43, 0
	s_mov_b32 s45, 0xc000
	s_mov_b32 s49, 0
	v_and_b32_e32 v58, 0xfffff9f, v13
	v_lshrrev_b32_e32 v59, 1, v13
	v_and_b32_e32 v13, 0x5f, v13
	s_movk_i32 s2, 0x50
	v_and_b32_e32 v59, 16, v59
	v_mad_u32_u24 v13, v13, s2, 0
	v_mul_lo_u32 v60, v38, s2
	v_mul_lo_u32 v58, v58, s2
	v_add_u32_e32 v189, v13, v59
	v_add_u32_e32 v13, 0, v196
	v_readlane_b32 s17, v250, 54
	v_mov_b32_e32 v0, 0
	v_lshlrev_b64 v[38:39], 10, v[38:39]
	v_add_u32_e32 v58, 0, v58
	v_lshlrev_b64 v[42:43], 10, v[42:43]
	v_lshlrev_b64 v[46:47], 10, v[46:47]
	v_lshlrev_b64 v[50:51], 10, v[50:51]
	v_add_u32_e32 v191, v13, v60
	s_mov_b32 s16, 64
	s_mov_b32 s17, 0
	v_mov_b32_e32 v1, v0
	v_mov_b32_e32 v2, v0
	v_mov_b32_e32 v3, v0
	v_mov_b32_e32 v4, v0
	v_mov_b32_e32 v5, v0
	v_mov_b32_e32 v6, v0
	v_mov_b32_e32 v7, v0
	v_mov_b32_e32 v8, v0
	v_mov_b32_e32 v9, v0
	v_mov_b32_e32 v10, v0
	v_mov_b32_e32 v11, v0
	v_mov_b32_e32 v12, v0
	v_lshlrev_b64 v[180:181], 1, v[38:39]
	v_add_u32_e32 v190, v58, v59
	v_lshlrev_b64 v[182:183], 1, v[42:43]
	v_lshlrev_b64 v[184:185], 1, v[46:47]
	v_lshlrev_b64 v[186:187], 1, v[50:51]
	v_mov_b32_e32 v13, v0
	v_mov_b32_e32 v38, v0
	v_mov_b32_e32 v39, v0
	v_mov_b32_e32 v14, v0
	v_mov_b32_e32 v15, v0
	v_mov_b32_e32 v16, v0
	v_mov_b32_e32 v17, v0
	v_mov_b32_e32 v18, v0
	v_mov_b32_e32 v19, v0
	v_mov_b32_e32 v20, v0
	v_mov_b32_e32 v21, v0
	v_mov_b32_e32 v22, v0
	v_mov_b32_e32 v23, v0
	v_mov_b32_e32 v24, v0
	v_mov_b32_e32 v25, v0
	v_mov_b32_e32 v26, v0
	v_mov_b32_e32 v27, v0
	v_mov_b32_e32 v28, v0
	v_mov_b32_e32 v29, v0
	v_mov_b32_e32 v30, v0
	v_mov_b32_e32 v31, v0
	v_mov_b32_e32 v32, v0
	v_mov_b32_e32 v33, v0
	v_mov_b32_e32 v34, v0
	v_mov_b32_e32 v35, v0
	v_mov_b32_e32 v36, v0
	v_mov_b32_e32 v37, v0
	v_mov_b32_e32 v40, v0
	v_mov_b32_e32 v41, v0
	v_mov_b32_e32 v42, v0
	v_mov_b32_e32 v43, v0
	v_mov_b32_e32 v44, v0
	v_mov_b32_e32 v45, v0
	v_mov_b32_e32 v46, v0
	v_mov_b32_e32 v47, v0
	v_mov_b32_e32 v48, v0
	v_mov_b32_e32 v49, v0
	v_mov_b32_e32 v50, v0
	v_mov_b32_e32 v51, v0
	v_mov_b32_e32 v52, v0
	v_mov_b32_e32 v53, v0
	v_mov_b32_e32 v54, v0
	v_mov_b32_e32 v55, v0
	v_mov_b32_e32 v56, v0
	v_mov_b32_e32 v57, v0
	v_mov_b32_e32 v58, v0
	v_mov_b32_e32 v59, v0
	v_mov_b32_e32 v60, v0
	v_mov_b32_e32 v61, v0
	v_mov_b32_e32 v62, v0
	v_mov_b32_e32 v63, v0
	v_mov_b32_e32 v64, v0
	v_mov_b32_e32 v65, v0
	v_mov_b32_e32 v66, v0
	v_mov_b32_e32 v67, v0
	v_mov_b32_e32 v68, v0
	v_mov_b32_e32 v69, v0
	v_mov_b32_e32 v70, v0
	v_mov_b32_e32 v71, v0
	v_mov_b32_e32 v72, v0
	v_mov_b32_e32 v73, v0
	v_mov_b32_e32 v74, v0
	v_mov_b32_e32 v75, v0
	v_mov_b32_e32 v76, v0
	v_mov_b32_e32 v77, v0
	v_mov_b32_e32 v78, v0
	v_mov_b32_e32 v79, v0
	v_mov_b32_e32 v80, v0
	v_mov_b32_e32 v81, v0
	v_mov_b32_e32 v82, v0
	v_mov_b32_e32 v83, v0
	v_mov_b32_e32 v84, v0
	v_mov_b32_e32 v85, v0
	v_mov_b32_e32 v86, v0
	v_mov_b32_e32 v87, v0
	v_mov_b32_e32 v88, v0
	v_mov_b32_e32 v89, v0
	v_mov_b32_e32 v90, v0
	v_mov_b32_e32 v91, v0
	v_mov_b32_e32 v92, v0
	v_mov_b32_e32 v93, v0
	v_mov_b32_e32 v94, v0
	v_mov_b32_e32 v95, v0
	v_mov_b32_e32 v96, v0
	v_mov_b32_e32 v97, v0
	v_mov_b32_e32 v98, v0
	v_mov_b32_e32 v99, v0
	v_mov_b32_e32 v100, v0
	v_mov_b32_e32 v101, v0
	v_mov_b32_e32 v102, v0
	v_mov_b32_e32 v103, v0
	v_mov_b32_e32 v104, v0
	v_mov_b32_e32 v105, v0
	v_mov_b32_e32 v106, v0
	v_mov_b32_e32 v107, v0
	v_mov_b32_e32 v108, v0
	v_mov_b32_e32 v109, v0
	v_mov_b32_e32 v110, v0
	v_mov_b32_e32 v111, v0
	v_mov_b32_e32 v112, v0
	v_mov_b32_e32 v113, v0
	v_mov_b32_e32 v114, v0
	v_mov_b32_e32 v115, v0
	v_mov_b32_e32 v116, v0
	v_mov_b32_e32 v117, v0
	v_mov_b32_e32 v118, v0
	v_mov_b32_e32 v119, v0
	v_mov_b32_e32 v120, v0
	v_mov_b32_e32 v121, v0
	v_mov_b32_e32 v122, v0
	v_mov_b32_e32 v123, v0
	v_mov_b32_e32 v124, v0
	v_mov_b32_e32 v125, v0
	v_mov_b32_e32 v126, v0
	v_mov_b32_e32 v127, v0
	v_readlane_b32 s18, v250, 55
	v_readlane_b32 s19, v250, 56
	v_readlane_b32 s20, v250, 57
	v_readlane_b32 s21, v250, 58
	v_readlane_b32 s24, v250, 61
	v_readlane_b32 s25, v250, 62
	v_readlane_b32 s28, v249, 1
	v_readlane_b32 s29, v249, 2
	v_readlane_b32 s30, v249, 3
	v_readlane_b32 s31, v249, 4
	s_waitcnt vmcnt(6)
	s_waitcnt lgkmcnt(0)
	v_readlane_b32 s44, v251, 5
	s_nop 0
	s_bitcmp1_b32 s44, 5
	s_cbranch_scc0 .Lnoprio_0
	s_setprio 2

.LBB0_77:
	ds_read_b128 v[128:131], v242
	ds_read_b128 v[144:147], v240
	ds_read_b128 v[132:135], v242 offset:1024
	ds_read_b128 v[148:151], v240 offset:1024
	ds_read_b128 v[136:139], v242 offset:2048
	ds_read_b128 v[140:143], v242 offset:3072
	ds_read_b128 v[152:155], v240 offset:2048
	ds_read_b128 v[156:159], v240 offset:3072
	ds_read_b128 v[160:163], v240 offset:4096
	ds_read_b128 v[164:167], v240 offset:5120
	ds_read_b128 v[168:171], v240 offset:6144
	ds_read_b128 v[172:175], v240 offset:7168
	s_waitcnt lgkmcnt(10)
	v_mfma_f32_16x16x32_bf16 v[112:115], v[128:131], v[144:147], v[112:115]
	s_add_u32 m0, s46, s45
	s_waitcnt lgkmcnt(9)
	v_mfma_f32_16x16x32_bf16 v[120:123], v[132:135], v[144:147], v[120:123]
	s_waitcnt lgkmcnt(8)
	v_mfma_f32_16x16x32_bf16 v[116:119], v[128:131], v[148:151], v[116:119]
	v_mfma_f32_16x16x32_bf16 v[124:127], v[132:135], v[148:151], v[124:127]
	global_load_lds_dwordx4 v234, s[40:41]
	s_waitcnt lgkmcnt(7)
	v_mfma_f32_16x16x32_bf16 v[96:99], v[136:139], v[144:147], v[96:99]
	s_add_u32 m0, m0, 0x400
	v_mfma_f32_16x16x32_bf16 v[100:103], v[136:139], v[148:151], v[100:103]
	s_waitcnt lgkmcnt(6)
	v_mfma_f32_16x16x32_bf16 v[104:107], v[140:143], v[144:147], v[104:107]
	v_mfma_f32_16x16x32_bf16 v[108:111], v[140:143], v[148:151], v[108:111]
	global_load_lds_dwordx4 v235, s[40:41]
	s_waitcnt lgkmcnt(5)
	v_mfma_f32_16x16x32_bf16 v[80:83], v[128:131], v[152:155], v[80:83]
	s_add_u32 m0, m0, 0x400
	v_mfma_f32_16x16x32_bf16 v[88:91], v[132:135], v[152:155], v[88:91]
	v_mfma_f32_16x16x32_bf16 v[64:67], v[136:139], v[152:155], v[64:67]
	v_mfma_f32_16x16x32_bf16 v[72:75], v[140:143], v[152:155], v[72:75]
	global_load_lds_dwordx4 v236, s[40:41]
	s_waitcnt lgkmcnt(4)
	v_mfma_f32_16x16x32_bf16 v[84:87], v[128:131], v[156:159], v[84:87]
	s_add_u32 m0, m0, 0x400
	v_mfma_f32_16x16x32_bf16 v[92:95], v[132:135], v[156:159], v[92:95]
	v_mfma_f32_16x16x32_bf16 v[68:71], v[136:139], v[156:159], v[68:71]
	v_mfma_f32_16x16x32_bf16 v[76:79], v[140:143], v[156:159], v[76:79]
	global_load_lds_dwordx4 v237, s[40:41]
	s_waitcnt lgkmcnt(3)
	v_mfma_f32_16x16x32_bf16 v[48:51], v[128:131], v[160:163], v[48:51]
	s_add_u32 m0, s47, s45
	v_mfma_f32_16x16x32_bf16 v[56:59], v[132:135], v[160:163], v[56:59]
	v_mfma_f32_16x16x32_bf16 v[32:35], v[136:139], v[160:163], v[32:35]
	v_mfma_f32_16x16x32_bf16 v[40:43], v[140:143], v[160:163], v[40:43]
	global_load_lds_dwordx4 v238, s[42:43]
	s_waitcnt lgkmcnt(2)
	v_mfma_f32_16x16x32_bf16 v[52:55], v[128:131], v[164:167], v[52:55]
	s_add_u32 m0, m0, 0x400
	v_mfma_f32_16x16x32_bf16 v[60:63], v[132:135], v[164:167], v[60:63]
	v_mfma_f32_16x16x32_bf16 v[36:39], v[136:139], v[164:167], v[36:39]
	v_mfma_f32_16x16x32_bf16 v[44:47], v[140:143], v[164:167], v[44:47]
	global_load_lds_dwordx4 v239, s[42:43]
	s_waitcnt lgkmcnt(1)
	v_mfma_f32_16x16x32_bf16 v[16:19], v[128:131], v[168:171], v[16:19]
	v_mfma_f32_16x16x32_bf16 v[24:27], v[132:135], v[168:171], v[24:27]
	s_mov_b32 s32, 0x6000
	s_cmp_eq_u32 s49, 0xc000
	s_cselect_b32 s32, 0xffff4000, s32
	s_add_u32 s49, s49, s32
	v_add_u32_e32 v240, s32, v240
	v_add_u32_e32 v242, s32, v242
	s_add_u32 s45, s45, 0x6000
	s_cmp_eq_u32 s45, 0x12000
	s_cselect_b32 s45, 0, s45
	s_add_u32 s40, s40, 64
	s_addc_u32 s41, s41, 0
	s_add_u32 s42, s42, 64
	s_addc_u32 s43, s43, 0
	v_mfma_f32_16x16x32_bf16 v[0:3], v[136:139], v[168:171], v[0:3]
	v_mfma_f32_16x16x32_bf16 v[8:11], v[140:143], v[168:171], v[8:11]
	s_waitcnt lgkmcnt(0)
	v_mfma_f32_16x16x32_bf16 v[20:23], v[128:131], v[172:175], v[20:23]
	v_mfma_f32_16x16x32_bf16 v[28:31], v[132:135], v[172:175], v[28:31]
	v_mfma_f32_16x16x32_bf16 v[4:7], v[136:139], v[172:175], v[4:7]
	v_mfma_f32_16x16x32_bf16 v[12:15], v[140:143], v[172:175], v[12:15]
	s_add_u32 s17, s17, 1
	s_waitcnt vmcnt(6)
	s_cmp_lt_u32 s17, 30
	s_barrier
	s_cbranch_scc1 .LBB0_77
.Lp7_tail:
	ds_read_b128 v[128:131], v242
	ds_read_b128 v[144:147], v240
	ds_read_b128 v[132:135], v242 offset:1024
	ds_read_b128 v[148:151], v240 offset:1024
	ds_read_b128 v[136:139], v242 offset:2048
	ds_read_b128 v[140:143], v242 offset:3072
	ds_read_b128 v[152:155], v240 offset:2048
	ds_read_b128 v[156:159], v240 offset:3072
	ds_read_b128 v[160:163], v240 offset:4096
	ds_read_b128 v[164:167], v240 offset:5120
	ds_read_b128 v[168:171], v240 offset:6144
	ds_read_b128 v[172:175], v240 offset:7168
	s_waitcnt lgkmcnt(10)
	v_mfma_f32_16x16x32_bf16 v[112:115], v[128:131], v[144:147], v[112:115]
	s_waitcnt lgkmcnt(9)
	v_mfma_f32_16x16x32_bf16 v[120:123], v[132:135], v[144:147], v[120:123]
	s_waitcnt lgkmcnt(8)
	v_mfma_f32_16x16x32_bf16 v[116:119], v[128:131], v[148:151], v[116:119]
	v_mfma_f32_16x16x32_bf16 v[124:127], v[132:135], v[148:151], v[124:127]
	s_waitcnt lgkmcnt(7)
	v_mfma_f32_16x16x32_bf16 v[96:99], v[136:139], v[144:147], v[96:99]
	v_mfma_f32_16x16x32_bf16 v[100:103], v[136:139], v[148:151], v[100:103]
	s_waitcnt lgkmcnt(6)
	v_mfma_f32_16x16x32_bf16 v[104:107], v[140:143], v[144:147], v[104:107]
	v_mfma_f32_16x16x32_bf16 v[108:111], v[140:143], v[148:151], v[108:111]
	s_waitcnt lgkmcnt(5)
	v_mfma_f32_16x16x32_bf16 v[80:83], v[128:131], v[152:155], v[80:83]
	v_mfma_f32_16x16x32_bf16 v[88:91], v[132:135], v[152:155], v[88:91]
	v_mfma_f32_16x16x32_bf16 v[64:67], v[136:139], v[152:155], v[64:67]
	v_mfma_f32_16x16x32_bf16 v[72:75], v[140:143], v[152:155], v[72:75]
	s_waitcnt lgkmcnt(4)
	v_mfma_f32_16x16x32_bf16 v[84:87], v[128:131], v[156:159], v[84:87]
	v_mfma_f32_16x16x32_bf16 v[92:95], v[132:135], v[156:159], v[92:95]
	v_mfma_f32_16x16x32_bf16 v[68:71], v[136:139], v[156:159], v[68:71]
	v_mfma_f32_16x16x32_bf16 v[76:79], v[140:143], v[156:159], v[76:79]
	s_waitcnt lgkmcnt(3)
	v_mfma_f32_16x16x32_bf16 v[48:51], v[128:131], v[160:163], v[48:51]
	v_mfma_f32_16x16x32_bf16 v[56:59], v[132:135], v[160:163], v[56:59]
	v_mfma_f32_16x16x32_bf16 v[32:35], v[136:139], v[160:163], v[32:35]
	v_mfma_f32_16x16x32_bf16 v[40:43], v[140:143], v[160:163], v[40:43]
	s_waitcnt lgkmcnt(2)
	v_mfma_f32_16x16x32_bf16 v[52:55], v[128:131], v[164:167], v[52:55]
	v_mfma_f32_16x16x32_bf16 v[60:63], v[132:135], v[164:167], v[60:63]
	v_mfma_f32_16x16x32_bf16 v[36:39], v[136:139], v[164:167], v[36:39]
	v_mfma_f32_16x16x32_bf16 v[44:47], v[140:143], v[164:167], v[44:47]
	s_waitcnt lgkmcnt(1)
	v_mfma_f32_16x16x32_bf16 v[16:19], v[128:131], v[168:171], v[16:19]
	v_mfma_f32_16x16x32_bf16 v[24:27], v[132:135], v[168:171], v[24:27]
	s_mov_b32 s32, 0x6000
	s_cmp_eq_u32 s49, 0xc000
	s_cselect_b32 s32, 0xffff4000, s32
	s_add_u32 s49, s49, s32
	v_add_u32_e32 v240, s32, v240
	v_add_u32_e32 v242, s32, v242
	v_mfma_f32_16x16x32_bf16 v[0:3], v[136:139], v[168:171], v[0:3]
	v_mfma_f32_16x16x32_bf16 v[8:11], v[140:143], v[168:171], v[8:11]
	s_waitcnt lgkmcnt(0)
	v_mfma_f32_16x16x32_bf16 v[20:23], v[128:131], v[172:175], v[20:23]
	v_mfma_f32_16x16x32_bf16 v[28:31], v[132:135], v[172:175], v[28:31]
	v_mfma_f32_16x16x32_bf16 v[4:7], v[136:139], v[172:175], v[4:7]
	v_mfma_f32_16x16x32_bf16 v[12:15], v[140:143], v[172:175], v[12:15]
	s_add_u32 s17, s17, 1
	s_waitcnt vmcnt(0)
	s_cmp_lt_u32 s17, 32
	s_barrier
	s_cbranch_scc1 .Lp7_tail
	s_nop 7
	s_nop 7
	v_permlane16_swap_b32_e32 v112, v116
	v_permlane16_swap_b32_e32 v113, v117
	v_permlane16_swap_b32_e32 v114, v118
	v_permlane16_swap_b32_e32 v115, v119
	v_permlane16_swap_b32_e32 v120, v124
	v_permlane16_swap_b32_e32 v121, v125
	v_permlane16_swap_b32_e32 v122, v126
	v_permlane16_swap_b32_e32 v123, v127
	v_permlane16_swap_b32_e32 v96, v100
	v_permlane16_swap_b32_e32 v97, v101
	v_permlane16_swap_b32_e32 v98, v102
	v_permlane16_swap_b32_e32 v99, v103
	v_permlane16_swap_b32_e32 v104, v108
	v_permlane16_swap_b32_e32 v105, v109
	v_permlane16_swap_b32_e32 v106, v110
	v_permlane16_swap_b32_e32 v107, v111
	v_permlane16_swap_b32_e32 v80, v84
	v_permlane16_swap_b32_e32 v81, v85
	v_permlane16_swap_b32_e32 v82, v86
	v_permlane16_swap_b32_e32 v83, v87
	v_permlane16_swap_b32_e32 v88, v92
	v_permlane16_swap_b32_e32 v89, v93
	v_permlane16_swap_b32_e32 v90, v94
	v_permlane16_swap_b32_e32 v91, v95
	v_permlane16_swap_b32_e32 v64, v68
	v_permlane16_swap_b32_e32 v65, v69
	v_permlane16_swap_b32_e32 v66, v70
	v_permlane16_swap_b32_e32 v67, v71
	v_permlane16_swap_b32_e32 v72, v76
	v_permlane16_swap_b32_e32 v73, v77
	v_permlane16_swap_b32_e32 v74, v78
	v_permlane16_swap_b32_e32 v75, v79
	v_permlane16_swap_b32_e32 v48, v52
	v_permlane16_swap_b32_e32 v49, v53
	v_permlane16_swap_b32_e32 v50, v54
	v_permlane16_swap_b32_e32 v51, v55
	v_permlane16_swap_b32_e32 v56, v60
	v_permlane16_swap_b32_e32 v57, v61
	v_permlane16_swap_b32_e32 v58, v62
	v_permlane16_swap_b32_e32 v59, v63
	v_permlane16_swap_b32_e32 v32, v36
	v_permlane16_swap_b32_e32 v33, v37
	v_permlane16_swap_b32_e32 v34, v38
	v_permlane16_swap_b32_e32 v35, v39
	v_permlane16_swap_b32_e32 v40, v44
	v_permlane16_swap_b32_e32 v41, v45
	v_permlane16_swap_b32_e32 v42, v46
	v_permlane16_swap_b32_e32 v43, v47
	v_permlane16_swap_b32_e32 v16, v20
	v_permlane16_swap_b32_e32 v17, v21
	v_permlane16_swap_b32_e32 v18, v22
	v_permlane16_swap_b32_e32 v19, v23
	v_permlane16_swap_b32_e32 v24, v28
	v_permlane16_swap_b32_e32 v25, v29
	v_permlane16_swap_b32_e32 v26, v30
	v_permlane16_swap_b32_e32 v27, v31
	v_permlane16_swap_b32_e32 v0, v4
	v_permlane16_swap_b32_e32 v1, v5
	v_permlane16_swap_b32_e32 v2, v6
	v_permlane16_swap_b32_e32 v3, v7
	v_permlane16_swap_b32_e32 v8, v12
	v_permlane16_swap_b32_e32 v9, v13
	v_permlane16_swap_b32_e32 v10, v14
	v_permlane16_swap_b32_e32 v11, v15
	v_permlane32_swap_b32_e32 v112, v116
	v_permlane32_swap_b32_e32 v113, v117
	v_permlane32_swap_b32_e32 v114, v118
	v_permlane32_swap_b32_e32 v115, v119
	v_permlane32_swap_b32_e32 v120, v124
	v_permlane32_swap_b32_e32 v121, v125
	v_permlane32_swap_b32_e32 v122, v126
	v_permlane32_swap_b32_e32 v123, v127
	v_permlane32_swap_b32_e32 v96, v100
	v_permlane32_swap_b32_e32 v97, v101
	v_permlane32_swap_b32_e32 v98, v102
	v_permlane32_swap_b32_e32 v99, v103
	v_permlane32_swap_b32_e32 v104, v108
	v_permlane32_swap_b32_e32 v105, v109
	v_permlane32_swap_b32_e32 v106, v110
	v_permlane32_swap_b32_e32 v107, v111
	v_permlane32_swap_b32_e32 v80, v84
	v_permlane32_swap_b32_e32 v81, v85
	v_permlane32_swap_b32_e32 v82, v86
	v_permlane32_swap_b32_e32 v83, v87
	v_permlane32_swap_b32_e32 v88, v92
	v_permlane32_swap_b32_e32 v89, v93
	v_permlane32_swap_b32_e32 v90, v94
	v_permlane32_swap_b32_e32 v91, v95
	v_permlane32_swap_b32_e32 v64, v68
	v_permlane32_swap_b32_e32 v65, v69
	v_permlane32_swap_b32_e32 v66, v70
	v_permlane32_swap_b32_e32 v67, v71
	v_permlane32_swap_b32_e32 v72, v76
	v_permlane32_swap_b32_e32 v73, v77
	v_permlane32_swap_b32_e32 v74, v78
	v_permlane32_swap_b32_e32 v75, v79
	v_permlane32_swap_b32_e32 v48, v52
	v_permlane32_swap_b32_e32 v49, v53
	v_permlane32_swap_b32_e32 v50, v54
	v_permlane32_swap_b32_e32 v51, v55
	v_permlane32_swap_b32_e32 v56, v60
	v_permlane32_swap_b32_e32 v57, v61
	v_permlane32_swap_b32_e32 v58, v62
	v_permlane32_swap_b32_e32 v59, v63
	v_permlane32_swap_b32_e32 v32, v36
	v_permlane32_swap_b32_e32 v33, v37
	v_permlane32_swap_b32_e32 v34, v38
	v_permlane32_swap_b32_e32 v35, v39
	v_permlane32_swap_b32_e32 v40, v44
	v_permlane32_swap_b32_e32 v41, v45
	v_permlane32_swap_b32_e32 v42, v46
	v_permlane32_swap_b32_e32 v43, v47
	v_permlane32_swap_b32_e32 v16, v20
	v_permlane32_swap_b32_e32 v17, v21
	v_permlane32_swap_b32_e32 v18, v22
	v_permlane32_swap_b32_e32 v19, v23
	v_permlane32_swap_b32_e32 v24, v28
	v_permlane32_swap_b32_e32 v25, v29
	v_permlane32_swap_b32_e32 v26, v30
	v_permlane32_swap_b32_e32 v27, v31
	v_permlane32_swap_b32_e32 v0, v4
	v_permlane32_swap_b32_e32 v1, v5
	v_permlane32_swap_b32_e32 v2, v6
	v_permlane32_swap_b32_e32 v3, v7
	v_permlane32_swap_b32_e32 v8, v12
	v_permlane32_swap_b32_e32 v9, v13
	v_permlane32_swap_b32_e32 v10, v14
	v_permlane32_swap_b32_e32 v11, v15
	s_setprio 0
	s_branch .LBB0_74

.LBB0_106:
	s_and_b32 s2, s2, 7
	v_readlane_b32 s4, v251, 7
	s_or_b32 s16, s2, s4
	s_lshl_b32 s4, s15, 7
	s_lshl_b32 s14, s16, 19
	v_mov_b32_e32 v56, v200
	s_add_u32 s6, s20, s14
	s_mov_b32 s5, s3
	s_addc_u32 s7, s21, 0
	v_ashrrev_i32_e32 v36, 2, v56
	v_lshlrev_b32_e32 v0, 3, v56
	s_lshl_b64 s[8:9], s[4:5], 11
	v_readlane_b32 s10, v249, 19
	s_waitcnt vmcnt(0)
	v_and_b32_e32 v188, 24, v0
	v_add_u32_e32 v44, 0x80, v36
	v_readlane_b32 s11, v249, 20
	s_add_u32 s8, s10, s8
	v_lshlrev_b32_e32 v196, 1, v188
	v_add_u32_e32 v40, 64, v36
	v_ashrrev_i32_e32 v45, 31, v44
	v_add_u32_e32 v48, 0xc0, v36
	s_addc_u32 s9, s11, s9
	v_lshl_add_u64 v[176:177], s[6:7], 0, v[196:197]
	v_ashrrev_i32_e32 v37, 31, v36
	v_ashrrev_i32_e32 v41, 31, v40
	v_lshlrev_b64 v[4:5], 11, v[44:45]
	v_ashrrev_i32_e32 v49, 31, v48
	v_lshlrev_b64 v[0:1], 11, v[36:37]
	v_lshlrev_b64 v[2:3], 11, v[40:41]
	v_lshl_add_u64 v[46:47], v[176:177], 0, v[4:5]
	v_lshlrev_b64 v[4:5], 11, v[48:49]
	v_lshl_add_u64 v[178:179], s[8:9], 0, v[196:197]
	v_lshl_add_u64 v[38:39], v[176:177], 0, v[0:1]
	v_lshl_add_u64 v[42:43], v[176:177], 0, v[2:3]
	v_lshl_add_u64 v[50:51], v[176:177], 0, v[4:5]
	v_lshl_add_u64 v[52:53], v[178:179], 0, v[0:1]
	v_lshl_add_u64 v[54:55], v[178:179], 0, v[2:3]
	v_and_b32_e32 v192, 63, v200
	v_readfirstlane_b32 s44, v200
	v_lshrrev_b32_e32 v193, 2, v192
	v_and_b32_e32 v194, 3, v192
	v_lshrrev_b32_e32 v201, 4, v192
	s_lshr_b32 s44, s44, 6
	v_xor_b32_e32 v206, v194, v201
	v_lshlrev_b32_e32 v206, 4, v206
	s_lshl_b32 s32, s44, 6
	v_add_u32_e32 v212, s32, v193
	v_lshlrev_b32_e32 v212, 11, v212
	v_add_u32_e32 v234, v212, v206
	v_add_u32_e32 v235, 0x8000, v234
	v_add_u32_e32 v236, 0x10000, v234
	v_add_u32_e32 v237, 0x18000, v234
	s_lshl_b32 s32, s44, 5
	v_add_u32_e32 v212, s32, v193
	v_lshlrev_b32_e32 v212, 11, v212
	v_add_u32_e32 v238, v212, v206
	v_add_u32_e32 v239, 0x8000, v238
	v_and_b32_e32 v193, 15, v192
	v_lshrrev_b32_e32 v194, 4, v192
	v_bfe_u32 v201, v192, 2, 2
	v_xor_b32_e32 v206, v194, v201
	v_lshlrev_b32_e32 v206, 4, v206
	v_lshl_add_u32 v206, v193, 6, v206
	s_lshr_b32 s32, s44, 1
	s_lshl_b32 s32, s32, 13
	v_add_u32_e32 v240, s32, v206
	v_xor_b32_e32 v241, 32, v240
	s_and_b32 s32, s44, 1
	s_lshl_b32 s32, s32, 12
	s_add_u32 s32, s32, 0x4000
	v_add_u32_e32 v242, s32, v206
	v_xor_b32_e32 v243, 32, v242
	s_lshl_b32 s46, s44, 12
	s_lshl_b32 s47, s44, 11
	s_add_u32 s47, s47, 0x4000
	s_mov_b32 s40, s6
	s_mov_b32 s41, s7
	s_mov_b32 s42, s8
	s_mov_b32 s43, s9
	s_add_u32 m0, s46, 0x0
	s_nop 0
	global_load_lds_dwordx4 v234, s[40:41]
	s_add_u32 m0, m0, 0x400
	s_nop 0
	global_load_lds_dwordx4 v235, s[40:41]
	s_add_u32 m0, m0, 0x400
	s_nop 0
	global_load_lds_dwordx4 v236, s[40:41]
	s_add_u32 m0, m0, 0x400
	s_nop 0
	global_load_lds_dwordx4 v237, s[40:41]
	s_add_u32 m0, s47, 0x0
	s_nop 0
	global_load_lds_dwordx4 v238, s[42:43]
	s_add_u32 m0, m0, 0x400
	s_nop 0
	global_load_lds_dwordx4 v239, s[42:43]
	s_add_u32 s40, s40, 64
	s_addc_u32 s41, s41, 0
	s_add_u32 s42, s42, 64
	s_addc_u32 s43, s43, 0
	s_add_u32 m0, s46, 0x6000
	s_nop 0
	global_load_lds_dwordx4 v234, s[40:41]
	s_add_u32 m0, m0, 0x400
	s_nop 0
	global_load_lds_dwordx4 v235, s[40:41]
	s_add_u32 m0, m0, 0x400
	s_nop 0
	global_load_lds_dwordx4 v236, s[40:41]
	s_add_u32 m0, m0, 0x400
	s_nop 0
	global_load_lds_dwordx4 v237, s[40:41]
	s_add_u32 m0, s47, 0x6000
	s_nop 0
	global_load_lds_dwordx4 v238, s[42:43]
	s_add_u32 m0, m0, 0x400
	s_nop 0
	global_load_lds_dwordx4 v239, s[42:43]
	s_add_u32 s40, s40, 64
	s_addc_u32 s41, s41, 0
	s_add_u32 s42, s42, 64
	s_addc_u32 s43, s43, 0
	s_mov_b32 s45, 0xc000
	s_mov_b32 s49, 0
	v_and_b32_e32 v57, 0xfffff9f, v56
	v_lshrrev_b32_e32 v58, 1, v56
	v_and_b32_e32 v56, 0x5f, v56
	s_movk_i32 s2, 0x50
	v_and_b32_e32 v58, 16, v58
	v_mad_u32_u24 v56, v56, s2, 0
	v_mul_lo_u32 v59, v36, s2
	v_mul_lo_u32 v57, v57, s2
	v_add_u32_e32 v189, v56, v58
	v_add_u32_e32 v56, 0, v196
	v_mov_b32_e32 v0, 0
	v_lshlrev_b64 v[36:37], 10, v[36:37]
	v_add_u32_e32 v57, 0, v57
	v_lshlrev_b64 v[40:41], 10, v[40:41]
	v_lshlrev_b64 v[44:45], 10, v[44:45]
	v_lshlrev_b64 v[48:49], 10, v[48:49]
	v_add_u32_e32 v191, v56, v59
	s_mov_b32 s5, 64
	s_mov_b32 s17, 0
	v_mov_b32_e32 v1, v0
	v_mov_b32_e32 v2, v0
	v_mov_b32_e32 v3, v0
	v_mov_b32_e32 v4, v0
	v_mov_b32_e32 v5, v0
	v_mov_b32_e32 v6, v0
	v_mov_b32_e32 v7, v0
	v_mov_b32_e32 v8, v0
	v_mov_b32_e32 v9, v0
	v_mov_b32_e32 v10, v0
	v_mov_b32_e32 v11, v0
	v_lshlrev_b64 v[180:181], 1, v[36:37]
	v_add_u32_e32 v190, v57, v58
	v_lshlrev_b64 v[182:183], 1, v[40:41]
	v_lshlrev_b64 v[184:185], 1, v[44:45]
	v_lshlrev_b64 v[186:187], 1, v[48:49]
	v_mov_b32_e32 v36, v0
	v_mov_b32_e32 v37, v0
	v_mov_b32_e32 v38, v0
	v_mov_b32_e32 v39, v0
	v_mov_b32_e32 v40, v0
	v_mov_b32_e32 v41, v0
	v_mov_b32_e32 v42, v0
	v_mov_b32_e32 v12, v0
	v_mov_b32_e32 v13, v0
	v_mov_b32_e32 v14, v0
	v_mov_b32_e32 v15, v0
	v_mov_b32_e32 v16, v0
	v_mov_b32_e32 v17, v0
	v_mov_b32_e32 v18, v0
	v_mov_b32_e32 v19, v0
	v_mov_b32_e32 v20, v0
	v_mov_b32_e32 v21, v0
	v_mov_b32_e32 v22, v0
	v_mov_b32_e32 v23, v0
	v_mov_b32_e32 v24, v0
	v_mov_b32_e32 v25, v0
	v_mov_b32_e32 v26, v0
	v_mov_b32_e32 v27, v0
	v_mov_b32_e32 v28, v0
	v_mov_b32_e32 v29, v0
	v_mov_b32_e32 v30, v0
	v_mov_b32_e32 v31, v0
	v_mov_b32_e32 v32, v0
	v_mov_b32_e32 v33, v0
	v_mov_b32_e32 v34, v0
	v_mov_b32_e32 v35, v0
	v_mov_b32_e32 v43, v0
	v_mov_b32_e32 v44, v0
	v_mov_b32_e32 v45, v0
	v_mov_b32_e32 v46, v0
	v_mov_b32_e32 v47, v0
	v_mov_b32_e32 v48, v0
	v_mov_b32_e32 v49, v0
	v_mov_b32_e32 v50, v0
	v_mov_b32_e32 v51, v0
	v_mov_b32_e32 v52, v0
	v_mov_b32_e32 v53, v0
	v_mov_b32_e32 v54, v0
	v_mov_b32_e32 v55, v0
	v_mov_b32_e32 v56, v0
	v_mov_b32_e32 v57, v0
	v_mov_b32_e32 v58, v0
	v_mov_b32_e32 v59, v0
	v_mov_b32_e32 v60, v0
	v_mov_b32_e32 v61, v0
	v_mov_b32_e32 v62, v0
	v_mov_b32_e32 v63, v0
	v_mov_b32_e32 v64, v0
	v_mov_b32_e32 v65, v0
	v_mov_b32_e32 v66, v0
	v_mov_b32_e32 v67, v0
	v_mov_b32_e32 v68, v0
	v_mov_b32_e32 v69, v0
	v_mov_b32_e32 v70, v0
	v_mov_b32_e32 v71, v0
	v_mov_b32_e32 v72, v0
	v_mov_b32_e32 v73, v0
	v_mov_b32_e32 v74, v0
	v_mov_b32_e32 v75, v0
	v_mov_b32_e32 v76, v0
	v_mov_b32_e32 v77, v0
	v_mov_b32_e32 v78, v0
	v_mov_b32_e32 v79, v0
	v_mov_b32_e32 v80, v0
	v_mov_b32_e32 v81, v0
	v_mov_b32_e32 v82, v0
	v_mov_b32_e32 v83, v0
	v_mov_b32_e32 v84, v0
	v_mov_b32_e32 v85, v0
	v_mov_b32_e32 v86, v0
	v_mov_b32_e32 v87, v0
	v_mov_b32_e32 v88, v0
	v_mov_b32_e32 v89, v0
	v_mov_b32_e32 v90, v0
	v_mov_b32_e32 v91, v0
	v_mov_b32_e32 v92, v0
	v_mov_b32_e32 v93, v0
	v_mov_b32_e32 v94, v0
	v_mov_b32_e32 v95, v0
	v_mov_b32_e32 v96, v0
	v_mov_b32_e32 v97, v0
	v_mov_b32_e32 v98, v0
	v_mov_b32_e32 v99, v0
	v_mov_b32_e32 v100, v0
	v_mov_b32_e32 v101, v0
	v_mov_b32_e32 v102, v0
	v_mov_b32_e32 v103, v0
	v_mov_b32_e32 v104, v0
	v_mov_b32_e32 v105, v0
	v_mov_b32_e32 v106, v0
	v_mov_b32_e32 v107, v0
	v_mov_b32_e32 v108, v0
	v_mov_b32_e32 v109, v0
	v_mov_b32_e32 v110, v0
	v_mov_b32_e32 v111, v0
	v_mov_b32_e32 v112, v0
	v_mov_b32_e32 v113, v0
	v_mov_b32_e32 v114, v0
	v_mov_b32_e32 v115, v0
	v_mov_b32_e32 v116, v0
	v_mov_b32_e32 v117, v0
	v_mov_b32_e32 v118, v0
	v_mov_b32_e32 v119, v0
	v_mov_b32_e32 v120, v0
	v_mov_b32_e32 v121, v0
	v_mov_b32_e32 v122, v0
	v_mov_b32_e32 v123, v0
	v_mov_b32_e32 v124, v0
	v_mov_b32_e32 v125, v0
	v_mov_b32_e32 v126, v0
	v_mov_b32_e32 v127, v0
	s_waitcnt vmcnt(6)
	s_waitcnt lgkmcnt(0)
	v_readlane_b32 s44, v251, 5
	s_nop 0
	s_bitcmp1_b32 s44, 5
	s_cbranch_scc0 .Lnoprio_2
	s_setprio 2
